# candL + one-time stagger at attention phase start: waves 4-7 sleep ~1.25 us after the entry barrier
# baseline (speedup 1.0000x reference)
; #define LAS __attribute__((address_space(3)))
; __device__ __forceinline__ float alibi_slope(int h) { return exp2f(-(float)(h + 1)); }
; __device__ __forceinline__ void p2_attention(const Args& a, LAS unsigned char* lds) {
;     const int tid = threadIdx.x, lane = tid & 63, wave = __builtin_amdgcn_readfirstlane(tid >> 6), G = gridDim.x, bid = blockIdx.x;
;     unsigned char* ws = a.ws; float* out = a.out;
;     const bf16_t* QA = (const bf16_t*)(ws + WS_QA); const bf16_t* KA = (const bf16_t*)(ws + WS_KA); const bf16_t* VA = (const bf16_t*)(ws + WS_VAT);
;     const bf16_t* QB = (const bf16_t*)(ws + WS_QB); const bf16_t* KB = (const bf16_t*)(ws + WS_KB); const bf16_t* VBN = (const bf16_t*)(ws + WS_VBT);
;     bf16_t* CAT = (bf16_t*)(ws + WS_CAT);
;     LAS unsigned* rb = (LAS unsigned*)(lds + LDS_BARW - 16);
;     if (tid < 2) rb[tid] = 0u;
;     __syncthreads();
;     {
;         constexpr int NWR = 8;
;         const int aw = wave;
;         const float kbA = wave_max(fabsf(a.in[9][lane])) * 8.0f * 1.01f, kbB = wave_max(fabsf(a.in[11][lane])) * 8.0f * 1.01f;
;         const int tq = lane & 31, g = lane >> 5;
;         LAS unsigned char* stg = lds + 141312 + aw * 2048;
;         unsigned ep = 0u;
;         for (int wt = bid * NWR + aw; wt < NB * 8 * (SEQ / 32); wt += G * NWR) {
;             const int b = wt >> 10, hq = (wt >> 7) & 7, T = wt & 127, kv = hq >> 2, i0 = 32 * T;
;             WT w; w.q = QB + ((size_t)(b * SEQ + i0)) * 512 + hq * 64; w.qstride = 512;
;             w.k = KB + ((size_t)b * SEQ) * 128 + kv * 64; w.v = VBN + ((size_t)b * SEQ) * 128 + kv * 64; w.kstride = 128;
;             w.i0 = i0; w.slope2 = alibi_slope(hq) * LOG2E;
;             const float sink2 = a.in[12][hq] * LOG2E;
.LBB0_628:
	s_cmp_lt_i32 s26, 3
	s_cselect_b64 s[12:13], -1, 0
	s_and_b64 s[0:1], s[12:13], s[0:1]
	s_andn2_b64 vcc, exec, s[0:1]
	v_cmp_gt_u32_e64 s[4:5], 2, v0
	s_cbranch_vccnz .LBB0_705
	s_load_dword s2, s[96:97], 0xb0
	v_readfirstlane_b32 s3, v0
	s_and_saveexec_b64 s[0:1], s[4:5]
	v_lshl_add_u32 v1, v0, 2, 0
	v_add_u32_e32 v1, 0x26be0, v1
	v_mov_b32_e32 v2, 0
	ds_write_b32 v1, v2
	s_or_b64 exec, exec, s[0:1]
	v_and_b32_e32 v1, 63, v0
	v_lshlrev_b32_e32 v126, 2, v1
	s_waitcnt lgkmcnt(0)
	s_barrier
	s_cmpk_lt_u32 s3, 0x100
	s_cbranch_scc1 .Lstag_p2
	s_sleep 45
.Lstag_p2:
	global_load_dword v2, v126, s[54:55]
	global_load_dword v3, v126, s[58:59]
	v_mbcnt_lo_u32_b32 v4, -1, 0
	v_mbcnt_hi_u32_b32 v4, -1, v4
	v_and_b32_e32 v5, 64, v4
	v_xor_b32_e32 v6, 32, v4
	v_add_u32_e32 v5, 64, v5
	v_cmp_lt_i32_e32 vcc, v6, v5
	v_xor_b32_e32 v7, 16, v4
	v_xor_b32_e32 v8, 8, v4
	v_cndmask_b32_e32 v6, v4, v6, vcc
	v_lshlrev_b32_e32 v127, 2, v6
	v_cmp_lt_i32_e32 vcc, v7, v5
	v_xor_b32_e32 v9, 4, v4
	v_xor_b32_e32 v10, 2, v4
	v_cndmask_b32_e32 v7, v4, v7, vcc
	v_lshlrev_b32_e32 v150, 2, v7
	v_cmp_lt_i32_e32 vcc, v8, v5
	v_xor_b32_e32 v11, 1, v4
	s_lshr_b32 s16, s3, 6
	v_cndmask_b32_e32 v8, v4, v8, vcc
	v_lshlrev_b32_e32 v8, 2, v8
	v_cmp_lt_i32_e32 vcc, v9, v5
	s_add_u32 s6, s24, 0x9946000
	s_addc_u32 s7, s25, 0
	v_cndmask_b32_e32 v9, v4, v9, vcc
	v_lshlrev_b32_e32 v9, 2, v9
	v_cmp_lt_i32_e32 vcc, v10, v5
	s_lshl_b32 s0, s16, 11
	s_lshl_b32 s1, s86, 3
	s_add_i32 s21, s0, 0
	s_add_i32 s14, s16, s1
	s_add_i32 s21, s21, 0x22800
	v_mov_b32_e32 v129, 0
	s_mov_b32 s9, 0
	v_and_b32_e32 v151, 31, v0
	v_bfe_u32 v142, v0, 5, 1
	v_lshrrev_b32_e32 v144, 2, v0
	v_and_b32_e32 v143, 19, v0
	s_cmpk_gt_i32 s14, 0xfff
	v_lshrrev_b32_e32 v148, 1, v0
	v_lshlrev_b32_e32 v149, 1, v0
	v_lshlrev_b32_e32 v147, 9, v0
	v_lshlrev_b32_e32 v146, 5, v0
	v_and_b32_e32 v145, 16, v0
	s_waitcnt vmcnt(1)
	v_and_b32_e32 v6, 0x7fffffff, v2
	s_waitcnt vmcnt(0)
	v_and_b32_e32 v12, 0x7fffffff, v3
	ds_bpermute_b32 v6, v127, v6
	ds_bpermute_b32 v12, v127, v12
	v_max_f32_e64 v2, |v2|, |v2|
	v_max_f32_e64 v3, |v3|, |v3|
	s_waitcnt lgkmcnt(1)
	v_max_f32_e32 v6, v6, v6
	s_waitcnt lgkmcnt(0)
	v_max_f32_e32 v7, v12, v12
	v_max_f32_e32 v2, v2, v6
	v_max_f32_e32 v3, v3, v7
	ds_bpermute_b32 v6, v150, v2
	ds_bpermute_b32 v7, v150, v3
	s_waitcnt lgkmcnt(1)
	v_max_f32_e32 v6, v6, v6
	s_waitcnt lgkmcnt(0)
	v_max_f32_e32 v7, v7, v7
	v_max_f32_e32 v2, v2, v6
	v_max_f32_e32 v3, v3, v7
	ds_bpermute_b32 v6, v8, v2
	ds_bpermute_b32 v7, v8, v3
	v_cndmask_b32_e32 v8, v4, v10, vcc
	v_cmp_lt_i32_e32 vcc, v11, v5
	v_lshlrev_b32_e32 v5, 2, v8
	s_waitcnt lgkmcnt(1)
	v_max_f32_e32 v6, v6, v6
	s_waitcnt lgkmcnt(0)
	v_max_f32_e32 v7, v7, v7
	v_max_f32_e32 v2, v2, v6
	v_max_f32_e32 v3, v3, v7
	ds_bpermute_b32 v6, v9, v2
	ds_bpermute_b32 v7, v9, v3
	v_cndmask_b32_e32 v4, v4, v11, vcc
	v_lshlrev_b32_e32 v4, 2, v4
	s_waitcnt lgkmcnt(1)
	v_max_f32_e32 v6, v6, v6
	s_waitcnt lgkmcnt(0)
	v_max_f32_e32 v7, v7, v7
	v_max_f32_e32 v2, v2, v6
	v_max_f32_e32 v3, v3, v7
	ds_bpermute_b32 v6, v5, v2
	ds_bpermute_b32 v5, v5, v3
	s_waitcnt lgkmcnt(1)
	v_max_f32_e32 v6, v6, v6
	s_waitcnt lgkmcnt(0)
	v_max_f32_e32 v5, v5, v5
	v_max_f32_e32 v152, v2, v6
	v_max_f32_e32 v2, v3, v5
	ds_bpermute_b32 v153, v4, v152
	ds_bpermute_b32 v3, v4, v2
	s_cbranch_scc1 .LBB0_636
	s_add_u32 s15, s24, 0x7fc6000
	s_waitcnt lgkmcnt(0)
	v_max_f32_e32 v3, v3, v3
	v_max_f32_e32 v2, v2, v2
	s_addc_u32 s17, s25, 0
	v_max_f32_e32 v2, v2, v3
	s_add_u32 s18, s24, 0x90c6000
	v_and_b32_e32 v3, 4, v148
	v_and_b32_e32 v5, 8, v149
	s_addc_u32 s19, s25, 0
	v_or3_b32 v155, v3, v143, v5
	v_lshlrev_b32_e32 v3, 4, v0
	v_lshlrev_b32_e32 v8, 2, v0
	v_mul_f32_e32 v2, 0x41000000, v2
	s_add_u32 s20, s24, 0x9506000
	v_and_b32_e32 v4, 8, v144
	v_and_b32_e32 v6, 48, v3
	v_and_b32_e32 v5, 0x400, v147
	v_and_b32_e32 v7, 0x3c0, v3
	v_and_b32_e32 v3, 0x2c0, v3
	v_and_or_b32 v8, v8, 12, v145
	v_mul_f32_e32 v154, 0x3f8147ae, v2
	s_addc_u32 s22, s25, 0
	v_lshlrev_b32_e32 v2, 9, v151
	v_add3_u32 v5, s21, v5, v7
	v_and_b32_e32 v7, 32, v146
	v_add_u32_e32 v3, s21, v3
	v_lshlrev_b32_e32 v9, 1, v8
	v_lshlrev_b32_e32 v8, 2, v142
	s_lshl_b32 s0, s86, 8
	s_lshl_b32 s1, s16, 5
	v_sub_u32_e32 v10, v151, v4
	v_bfe_u32 v156, v0, 2, 4
	s_lshl_b32 s23, s2, 3
	v_or_b32_e32 v157, 0xffffff80, v4
	s_add_i32 s28, s0, s1
	s_lshl_b32 s29, s2, 8
	v_add_u32_e32 v158, 0x69, v10
	s_mov_b32 s30, 0x42fc0000
	v_lshlrev_b32_e32 v130, 1, v2
	v_lshlrev_b32_e32 v132, 1, v4
	s_mov_b32 s31, 0xf800000
	v_mov_b32_e32 v159, 0x260
	v_lshlrev_b32_e32 v134, 1, v6
	s_movk_i32 s33, 0x81
	s_movk_i32 s34, 0xffef
	s_movk_i32 s35, 0xffee
	s_movk_i32 s48, 0xffed
	s_movk_i32 s49, 0xffec
	s_movk_i32 s50, 0xffeb
	s_movk_i32 s51, 0xffea
	s_movk_i32 s52, 0xffe9
	s_movk_i32 s53, 0xffe8
	v_add_u32_e32 v160, v5, v7
	v_add_u32_e32 v161, v3, v9
	v_lshlrev_b32_e32 v136, 1, v8
	v_mov_b32_e32 v162, 0x42800000
	v_mov_b32_e32 v131, v129
	v_mov_b32_e32 v133, v129
	v_mov_b32_e32 v135, v129
